# layer-1 ffn1 gate/up conversion done in layer-0 gate/up-2 tail (P0 of layer 1 empty)
# baseline (speedup 1.0000x reference)
; #define LAS __attribute__((address_space(3)))
; #define PHASE_ENV unsigned char* ws = opq_ptr(p.ws); const int G = opq_int((int)gridDim.x), ngw = G * 8; (void)ws; (void)ngw
; template <int MAP, bool HASG = false, bool PERMW = false>
; __device__ __forceinline__ void transpose_mat(const float* W, int K, int N, bf16_t* WT, LAS float* scr, int gw, int ngw, int lane, const float* gk = nullptr) {
;     const int nitems = (K / 64) * (N / 32);
;     int it = gw;
;     if (it >= nitems) return;
;     float wv[32];
;     tr_load(W, N, it, lane, wv);
; __global__ void __launch_bounds__(512, 2) mega_fwd(Params p) {
;     ...
;             PHASE_IDS; PHASE_ENV;
;             LAS float* scr = (LAS float*)(lds + wave * 8448);
;             transpose_mat<1, true, true>(p.in[2] + (size_t)l * D * DFF, D, DFF, P_W(WS_WGU1), scr, gw, ngw, lane, p.in[1] + l * D);
.LBB0_23:
	v_mov_b32_e32 v133, v234
	s_mov_b32 s9, s91
	v_readfirstlane_b32 s0, v133
	s_ashr_i32 s22, s0, 6
	v_readlane_b32 s0, v254, 19
	s_add_i32 s6, s22, s0
	s_ashr_i32 s24, s9, 31
	s_add_u32 s7, s76, s9
	s_mov_b32 s23, s78
	s_mul_i32 s0, s22, 0x2100
	v_and_b32_e32 v132, 63, v133
	s_addc_u32 s25, s77, s24
	s_lshl_b32 s8, s23, 3
	s_add_i32 s26, s0, 0
	s_lshl_b32 s0, s36, 11
	s_cmpk_lt_i32 s6, 0x1600
	v_lshrrev_b32_e32 v134, 5, v132
	v_and_b32_e32 v44, 31, v133
	v_lshrrev_b32_e32 v0, 1, v132
	s_mul_i32 s90, s36, 0xb00000
	s_mov_b32 s1, s91
	s_cselect_b64 s[4:5], -1, 0
	s_cmpk_gt_i32 s6, 0x15ff
	s_mul_hi_i32 s27, s6, 0x2e8ba2e9
	v_bfe_u32 v135, v133, 2, 1
	v_lshlrev_b32_e32 v46, 2, v44
	v_and_b32_e32 v45, 28, v0
	v_and_b32_e32 v137, 16, v0
	v_mul_u32_u24_e32 v136, 0x84, v134
	s_cbranch_scc1 .LBB0_36
	s_cmp_lg_u32 s36, 0
	s_cbranch_scc1 .LBB0_36
; __device__ __forceinline__ void tr_load(const float* W, int N, int item, int lane, float (&wv)[32]) {
;     const int nblk = N / 32, kb = item / nblk, nb = item % nblk, k0 = 64 * kb, n0 = 32 * nb;
; #pragma unroll
;     for (int i = 0; i < 32; ++i) { const int kk = 2 * i + (lane >> 5); wv[i] = __builtin_nontemporal_load(W + (size_t)(k0 + kk) * N + n0 + (lane & 31)); }
; }
	v_readlane_b32 s56, v254, 60
	s_lshl_b64 s[10:11], s[0:1], 2
	v_readlane_b32 s58, v254, 62
	v_readlane_b32 s59, v254, 63
	s_add_u32 s16, s58, s10
	v_readlane_b32 s60, v255, 0
	s_addc_u32 s17, s59, s11
	s_lshl_b64 s[10:11], s[90:91], 2
	v_readlane_b32 s61, v255, 1
	s_add_u32 s18, s60, s10
	s_addc_u32 s19, s61, s11
	s_lshr_b32 s12, s27, 31
	s_ashr_i32 s13, s27, 5
	s_add_i32 s13, s13, s12
	s_mul_i32 s12, s13, 0xb0
	s_sub_i32 s12, s6, s12
	s_lshl_b32 s12, s12, 5
	v_lshl_or_b32 v34, s13, 6, v134
	s_ashr_i32 s13, s12, 31
	s_lshl_b64 s[14:15], s[12:13], 2
	s_add_u32 s12, s18, s14
	s_addc_u32 s13, s19, s15
	v_mov_b32_e32 v47, v193
	v_lshl_add_u64 v[32:33], s[12:13], 0, v[46:47]
	v_mad_i64_i32 v[0:1], s[12:13], v34, s55, v[32:33]
	global_load_dword v0, v[0:1], off nt
	v_or_b32_e32 v1, 2, v34
	v_mad_i64_i32 v[2:3], s[12:13], v1, s55, v[32:33]
	v_mad_i64_i32 v[52:53], s[12:13], v1, s55, 0
	global_load_dword v1, v[2:3], off nt
	v_or_b32_e32 v2, 4, v34
	v_mad_i64_i32 v[54:55], s[12:13], v2, s55, 0
	v_mad_i64_i32 v[2:3], s[12:13], v2, s55, v[32:33]
	global_load_dword v2, v[2:3], off nt
	v_or_b32_e32 v3, 6, v34
	v_mad_i64_i32 v[4:5], s[12:13], v3, s55, v[32:33]
	v_mad_i64_i32 v[56:57], s[12:13], v3, s55, 0
	global_load_dword v3, v[4:5], off nt
	v_or_b32_e32 v4, 8, v34
	v_mad_i64_i32 v[58:59], s[12:13], v4, s55, 0
	v_mad_i64_i32 v[4:5], s[12:13], v4, s55, v[32:33]
	global_load_dword v4, v[4:5], off nt
	v_or_b32_e32 v5, 10, v34
	v_mad_i64_i32 v[6:7], s[12:13], v5, s55, v[32:33]
	v_mad_i64_i32 v[60:61], s[12:13], v5, s55, 0
	global_load_dword v5, v[6:7], off nt
	v_or_b32_e32 v6, 12, v34
	v_mad_i64_i32 v[62:63], s[12:13], v6, s55, 0
	v_mad_i64_i32 v[6:7], s[12:13], v6, s55, v[32:33]
	global_load_dword v6, v[6:7], off nt
	v_or_b32_e32 v7, 14, v34
	v_mad_i64_i32 v[8:9], s[12:13], v7, s55, v[32:33]
	v_mad_i64_i32 v[64:65], s[12:13], v7, s55, 0
	global_load_dword v7, v[8:9], off nt
	v_or_b32_e32 v8, 16, v34
	v_mad_i64_i32 v[66:67], s[12:13], v8, s55, 0
	v_mad_i64_i32 v[8:9], s[12:13], v8, s55, v[32:33]
	global_load_dword v8, v[8:9], off nt
	v_or_b32_e32 v9, 18, v34
	v_mad_i64_i32 v[10:11], s[12:13], v9, s55, v[32:33]
	v_mad_i64_i32 v[68:69], s[12:13], v9, s55, 0
	global_load_dword v9, v[10:11], off nt
	v_or_b32_e32 v10, 20, v34
	v_mad_i64_i32 v[70:71], s[12:13], v10, s55, 0
	v_mad_i64_i32 v[10:11], s[12:13], v10, s55, v[32:33]
	global_load_dword v10, v[10:11], off nt
	v_or_b32_e32 v11, 22, v34
	v_mad_i64_i32 v[12:13], s[12:13], v11, s55, v[32:33]
	v_mad_i64_i32 v[72:73], s[12:13], v11, s55, 0
	global_load_dword v11, v[12:13], off nt
	v_or_b32_e32 v12, 24, v34
	v_mad_i64_i32 v[74:75], s[12:13], v12, s55, 0
	v_mad_i64_i32 v[12:13], s[12:13], v12, s55, v[32:33]
	global_load_dword v12, v[12:13], off nt
	v_or_b32_e32 v13, 26, v34
	v_mad_i64_i32 v[14:15], s[12:13], v13, s55, v[32:33]
	v_mad_i64_i32 v[76:77], s[12:13], v13, s55, 0
	global_load_dword v13, v[14:15], off nt
	v_or_b32_e32 v14, 28, v34
	v_mad_i64_i32 v[78:79], s[12:13], v14, s55, 0
	v_mad_i64_i32 v[14:15], s[12:13], v14, s55, v[32:33]
	global_load_dword v14, v[14:15], off nt
	v_or_b32_e32 v15, 30, v34
	v_mad_i64_i32 v[16:17], s[12:13], v15, s55, v[32:33]
	v_mad_i64_i32 v[80:81], s[12:13], v15, s55, 0
	global_load_dword v15, v[16:17], off nt
	v_or_b32_e32 v16, 32, v34
	v_mad_i64_i32 v[82:83], s[12:13], v16, s55, 0
	v_mad_i64_i32 v[16:17], s[12:13], v16, s55, v[32:33]
	global_load_dword v16, v[16:17], off nt
	v_or_b32_e32 v17, 34, v34
	v_mad_i64_i32 v[18:19], s[12:13], v17, s55, v[32:33]
	v_mad_i64_i32 v[84:85], s[12:13], v17, s55, 0
	global_load_dword v17, v[18:19], off nt
	v_or_b32_e32 v18, 36, v34
	v_mad_i64_i32 v[86:87], s[12:13], v18, s55, 0
	v_mad_i64_i32 v[18:19], s[12:13], v18, s55, v[32:33]
	global_load_dword v18, v[18:19], off nt
	v_or_b32_e32 v19, 38, v34
	v_mad_i64_i32 v[20:21], s[12:13], v19, s55, v[32:33]
	v_mad_i64_i32 v[88:89], s[12:13], v19, s55, 0
	global_load_dword v19, v[20:21], off nt
	v_or_b32_e32 v20, 40, v34
	v_mad_i64_i32 v[90:91], s[12:13], v20, s55, 0
	v_mad_i64_i32 v[20:21], s[12:13], v20, s55, v[32:33]
	global_load_dword v20, v[20:21], off nt
	v_or_b32_e32 v21, 42, v34
	v_mad_i64_i32 v[22:23], s[12:13], v21, s55, v[32:33]
	v_mad_i64_i32 v[92:93], s[12:13], v21, s55, 0
	global_load_dword v21, v[22:23], off nt
	v_or_b32_e32 v22, 44, v34
	v_mad_i64_i32 v[94:95], s[12:13], v22, s55, 0
	v_mad_i64_i32 v[22:23], s[12:13], v22, s55, v[32:33]
	global_load_dword v22, v[22:23], off nt
	v_or_b32_e32 v23, 46, v34
	v_mad_i64_i32 v[24:25], s[12:13], v23, s55, v[32:33]
	v_mad_i64_i32 v[96:97], s[12:13], v23, s55, 0
	global_load_dword v23, v[24:25], off nt
	v_or_b32_e32 v24, 48, v34
	v_mad_i64_i32 v[98:99], s[12:13], v24, s55, 0
	v_mad_i64_i32 v[24:25], s[12:13], v24, s55, v[32:33]
	global_load_dword v24, v[24:25], off nt
	v_or_b32_e32 v25, 50, v34
	v_mad_i64_i32 v[26:27], s[12:13], v25, s55, v[32:33]
	v_mad_i64_i32 v[100:101], s[12:13], v25, s55, 0
	global_load_dword v25, v[26:27], off nt
	v_or_b32_e32 v26, 52, v34
	v_mad_i64_i32 v[102:103], s[12:13], v26, s55, 0
	v_mad_i64_i32 v[26:27], s[12:13], v26, s55, v[32:33]
	global_load_dword v26, v[26:27], off nt
	v_or_b32_e32 v27, 54, v34
	v_mad_i64_i32 v[28:29], s[12:13], v27, s55, v[32:33]
	v_mad_i64_i32 v[104:105], s[12:13], v27, s55, 0
	global_load_dword v27, v[28:29], off nt
	v_or_b32_e32 v28, 56, v34
	v_mad_i64_i32 v[106:107], s[12:13], v28, s55, 0
	v_mad_i64_i32 v[28:29], s[12:13], v28, s55, v[32:33]
	global_load_dword v28, v[28:29], off nt
	v_or_b32_e32 v29, 58, v34
	v_mad_i64_i32 v[30:31], s[12:13], v29, s55, v[32:33]
	v_mad_i64_i32 v[108:109], s[12:13], v29, s55, 0
	global_load_dword v29, v[30:31], off nt
	v_or_b32_e32 v30, 60, v34
	v_mad_i64_i32 v[110:111], s[12:13], v30, s55, 0
	v_mad_i64_i32 v[30:31], s[12:13], v30, s55, v[32:33]
	global_load_dword v30, v[30:31], off nt
	v_or_b32_e32 v31, 62, v34
	v_mad_i64_i32 v[32:33], s[12:13], v31, s55, v[32:33]
	v_mad_i64_i32 v[112:113], s[12:13], v31, s55, 0
	global_load_dword v31, v[32:33], off nt
	v_lshlrev_b32_e32 v33, 3, v132
	v_mad_i64_i32 v[50:51], s[12:13], v34, s55, 0
	v_and_b32_e32 v34, 56, v33
	v_lshlrev_b32_e32 v192, 2, v34
	v_mul_u32_u24_e32 v34, 0x84, v34
	v_lshl_add_u64 v[114:115], s[18:19], 0, v[46:47]
	v_add3_u32 v47, s26, v34, v45
	v_lshlrev_b32_e32 v34, 4, v132
	v_add_u32_e32 v32, s26, v46
	v_and_b32_e32 v138, 48, v34
	s_lshl_b32 s13, s6, 5
	v_lshl_add_u64 v[48:49], s[16:17], 0, v[192:193]
	v_and_or_b32 v147, v33, s86, v138
	s_lshl_b32 s12, s8, 5
	v_add_u32_e32 v139, v32, v136
	s_mov_b32 s20, s13
	s_mov_b32 s21, s6
	v_readlane_b32 s57, v254, 61
	v_readlane_b32 s62, v255, 2
	v_readlane_b32 s63, v255, 3
	v_readlane_b32 s64, v255, 4
	v_readlane_b32 s65, v255, 5
	v_readlane_b32 s66, v255, 6
	v_readlane_b32 s67, v255, 7
	v_readlane_b32 s68, v255, 8
	v_readlane_b32 s69, v255, 9
	v_readlane_b32 s70, v255, 10
	v_readlane_b32 s71, v255, 11
	s_branch .LBB0_26

; __device__ __forceinline__ void tr_load(const float* W, int N, int item, int lane, float (&wv)[32]) {
;     const int nblk = N / 32, kb = item / nblk, nb = item % nblk, k0 = 64 * kb, n0 = 32 * nb;
; #pragma unroll
;     for (int i = 0; i < 32; ++i) { const int kk = 2 * i + (lane >> 5); wv[i] = __builtin_nontemporal_load(W + (size_t)(k0 + kk) * N + n0 + (lane & 31)); }
; }
; template <int MAP, bool HASG, bool PERMW>
; __device__ __forceinline__ void tr_store(int K, int N, bf16_t* WT, LAS float* scr, int item, int lane, const float* gk) {
;     const int nblk = N / 32, kb = item / nblk, nb = item % nblk, k0 = 64 * kb, n0 = 32 * nb;
;     asm volatile("s_waitcnt lgkmcnt(0)" ::: "memory");
;     const int c = lane & 7;
;     f32x4 g0 = {1.f, 1.f, 1.f, 1.f}, g1 = {1.f, 1.f, 1.f, 1.f};
;     if (HASG) { g0 = *(const f32x4*)(gk + k0 + 8 * c); g1 = *(const f32x4*)(gk + k0 + 8 * c + 4); }
; #pragma unroll
;     for (int j = 0; j < 4; ++j) { const int n = (lane >> 3) + 8 * j; const LAS float* s = scr + (8 * c) * 33 + n;
;         u32x4 o; o.x = pk2(s[0 * 33] * g0[0], s[1 * 33] * g0[1]); o.y = pk2(s[2 * 33] * g0[2], s[3 * 33] * g0[3]); o.z = pk2(s[4 * 33] * g1[0], s[5 * 33] * g1[1]); o.w = pk2(s[6 * 33] * g1[2], s[7 * 33] * g1[3]);
;         const int wr_ = rowmap<MAP>(n0 + n), slot_ = PERMW ? ((wr_ & ~31) + invperm32(wr_ & 31)) : wr_;
;         *(u32x4*)((char*)WT + tiled_off(slot_, k0 + 8 * c, K / 64)) = o; }
;     asm volatile("s_waitcnt lgkmcnt(0)" ::: "memory");
; }
; template <int MAP, bool HASG = false, bool PERMW = false>
; __device__ __forceinline__ void transpose_mat(const float* W, int K, int N, bf16_t* WT, LAS float* scr, int gw, int ngw, int lane, const float* gk = nullptr) {
;     const int nitems = (K / 64) * (N / 32);
;     int it = gw;
;     if (it >= nitems) return;
;     float wv[32];
;     tr_load(W, N, it, lane, wv);
;     for (;;) {
;         __builtin_amdgcn_sched_barrier(0);
; #pragma unroll
;         for (int i = 0; i < 32; ++i) { const int kk = 2 * i + (lane >> 5); scr[kk * 33 + (lane & 31)] = wv[i]; }
;         __builtin_amdgcn_sched_barrier(0);
;         const int nx = it + ngw;
;         if (nx < nitems) tr_load(W, N, nx, lane, wv);
;         __builtin_amdgcn_sched_barrier(0);
;         tr_store<MAP, HASG, PERMW>(K, N, WT, scr, it, lane, gk);
;         if (nx >= nitems) break;
;         it = nx;
;     }
; }
.Ltc2a_exit:
	s_cmp_lg_u32 s60, 0
	s_cbranch_scc1 .Ltc2_nonext
	v_readlane_b32 s4, v255, 0
	v_readlane_b32 s5, v255, 1
	v_readlane_b32 s20, v254, 62
	v_readlane_b32 s21, v254, 63
	s_nop 3
	s_andn2_b32 s6, 0x2c00000, s60
	s_add_u32 s4, s4, s6
	s_addc_u32 s5, s5, 0
	s_andn2_b32 s6, 0x2000, s60
	s_add_u32 s20, s20, s6
	s_addc_u32 s21, s21, 0
	s_add_u32 s6, s76, 0x0
	s_addc_u32 s7, s77, 0
	s_mov_b32 s9, s18
	s_cmpk_ge_u32 s9, 0x1600
	s_cbranch_scc1 .Ltc2b_exit
	s_mul_hi_u32 s11, s9, 0x2e8ba2e9
	s_lshr_b32 s11, s11, 5
	s_mul_i32 s12, s11, 0xb0
	s_sub_u32 s12, s9, s12
	s_mul_i32 s13, s11, 0x160000
	s_lshl_b32 s14, s12, 7
	s_add_u32 s13, s13, s14
	s_add_u32 s14, s4, s13
	s_addc_u32 s15, s5, 0
	global_load_dword v16, v15, s[14:15] nt
	s_add_u32 s14, s14, 0xb000
	s_addc_u32 s15, s15, 0
	global_load_dword v17, v15, s[14:15] nt
	s_add_u32 s14, s14, 0xb000
	s_addc_u32 s15, s15, 0
	global_load_dword v18, v15, s[14:15] nt
	s_add_u32 s14, s14, 0xb000
	s_addc_u32 s15, s15, 0
	global_load_dword v19, v15, s[14:15] nt
	s_add_u32 s14, s14, 0xb000
	s_addc_u32 s15, s15, 0
	global_load_dword v20, v15, s[14:15] nt
	s_add_u32 s14, s14, 0xb000
	s_addc_u32 s15, s15, 0
	global_load_dword v21, v15, s[14:15] nt
	s_add_u32 s14, s14, 0xb000
	s_addc_u32 s15, s15, 0
	global_load_dword v22, v15, s[14:15] nt
	s_add_u32 s14, s14, 0xb000
	s_addc_u32 s15, s15, 0
	global_load_dword v23, v15, s[14:15] nt
	s_add_u32 s14, s14, 0xb000
	s_addc_u32 s15, s15, 0
	global_load_dword v24, v15, s[14:15] nt
	s_add_u32 s14, s14, 0xb000
	s_addc_u32 s15, s15, 0
	global_load_dword v25, v15, s[14:15] nt
	s_add_u32 s14, s14, 0xb000
	s_addc_u32 s15, s15, 0
	global_load_dword v26, v15, s[14:15] nt
	s_add_u32 s14, s14, 0xb000
	s_addc_u32 s15, s15, 0
	global_load_dword v27, v15, s[14:15] nt
	s_add_u32 s14, s14, 0xb000
	s_addc_u32 s15, s15, 0
	global_load_dword v28, v15, s[14:15] nt
	s_add_u32 s14, s14, 0xb000
	s_addc_u32 s15, s15, 0
	global_load_dword v29, v15, s[14:15] nt
	s_add_u32 s14, s14, 0xb000
	s_addc_u32 s15, s15, 0
	global_load_dword v30, v15, s[14:15] nt
	s_add_u32 s14, s14, 0xb000
	s_addc_u32 s15, s15, 0
	global_load_dword v31, v15, s[14:15] nt
	s_add_u32 s14, s14, 0xb000
	s_addc_u32 s15, s15, 0
	global_load_dword v32, v15, s[14:15] nt
	s_add_u32 s14, s14, 0xb000
	s_addc_u32 s15, s15, 0
	global_load_dword v33, v15, s[14:15] nt
	s_add_u32 s14, s14, 0xb000
	s_addc_u32 s15, s15, 0
	global_load_dword v34, v15, s[14:15] nt
	s_add_u32 s14, s14, 0xb000
	s_addc_u32 s15, s15, 0
	global_load_dword v35, v15, s[14:15] nt
	s_add_u32 s14, s14, 0xb000
	s_addc_u32 s15, s15, 0
	global_load_dword v36, v15, s[14:15] nt
	s_add_u32 s14, s14, 0xb000
	s_addc_u32 s15, s15, 0
	global_load_dword v37, v15, s[14:15] nt
	s_add_u32 s14, s14, 0xb000
	s_addc_u32 s15, s15, 0
	global_load_dword v38, v15, s[14:15] nt
	s_add_u32 s14, s14, 0xb000
	s_addc_u32 s15, s15, 0
	global_load_dword v39, v15, s[14:15] nt
	s_add_u32 s14, s14, 0xb000
	s_addc_u32 s15, s15, 0
	global_load_dword v40, v15, s[14:15] nt
	s_add_u32 s14, s14, 0xb000
	s_addc_u32 s15, s15, 0
	global_load_dword v41, v15, s[14:15] nt
	s_add_u32 s14, s14, 0xb000
	s_addc_u32 s15, s15, 0
	global_load_dword v42, v15, s[14:15] nt
	s_add_u32 s14, s14, 0xb000
	s_addc_u32 s15, s15, 0
	global_load_dword v43, v15, s[14:15] nt
	s_add_u32 s14, s14, 0xb000
	s_addc_u32 s15, s15, 0
	global_load_dword v44, v15, s[14:15] nt
	s_add_u32 s14, s14, 0xb000
	s_addc_u32 s15, s15, 0
	global_load_dword v45, v15, s[14:15] nt
	s_add_u32 s14, s14, 0xb000
	s_addc_u32 s15, s15, 0
	global_load_dword v46, v15, s[14:15] nt
	s_add_u32 s14, s14, 0xb000
	s_addc_u32 s15, s15, 0
	global_load_dword v47, v15, s[14:15] nt
	s_lshl_b32 s14, s11, 8
	s_add_u32 s14, s20, s14
	s_addc_u32 s15, s21, 0
	global_load_dwordx4 v[80:83], v14, s[14:15]
	global_load_dwordx4 v[84:87], v14, s[14:15] offset:16
	s_lshr_b32 s16, s12, 2
	s_lshl_b32 s16, s16, 1
	s_lshl_b32 s16, s16, 5
	s_add_u32 s16, s16, s11
	s_lshl_b32 s16, s16, 14
	s_and_b32 s17, s12, 3
	s_lshl_b32 s17, s17, 12
	s_add_u32 s16, s16, s17
	s_add_u32 s16, s6, s16
	s_addc_u32 s17, s7, 0

; __device__ __forceinline__ void tr_load(const float* W, int N, int item, int lane, float (&wv)[32]) {
;     const int nblk = N / 32, kb = item / nblk, nb = item % nblk, k0 = 64 * kb, n0 = 32 * nb;
; #pragma unroll
;     for (int i = 0; i < 32; ++i) { const int kk = 2 * i + (lane >> 5); wv[i] = __builtin_nontemporal_load(W + (size_t)(k0 + kk) * N + n0 + (lane & 31)); }
; }
; template <int MAP, bool HASG, bool PERMW>
; __device__ __forceinline__ void tr_store(int K, int N, bf16_t* WT, LAS float* scr, int item, int lane, const float* gk) {
;     const int nblk = N / 32, kb = item / nblk, nb = item % nblk, k0 = 64 * kb, n0 = 32 * nb;
;     asm volatile("s_waitcnt lgkmcnt(0)" ::: "memory");
;     const int c = lane & 7;
;     f32x4 g0 = {1.f, 1.f, 1.f, 1.f}, g1 = {1.f, 1.f, 1.f, 1.f};
;     if (HASG) { g0 = *(const f32x4*)(gk + k0 + 8 * c); g1 = *(const f32x4*)(gk + k0 + 8 * c + 4); }
; #pragma unroll
;     for (int j = 0; j < 4; ++j) { const int n = (lane >> 3) + 8 * j; const LAS float* s = scr + (8 * c) * 33 + n;
;         u32x4 o; o.x = pk2(s[0 * 33] * g0[0], s[1 * 33] * g0[1]); o.y = pk2(s[2 * 33] * g0[2], s[3 * 33] * g0[3]); o.z = pk2(s[4 * 33] * g1[0], s[5 * 33] * g1[1]); o.w = pk2(s[6 * 33] * g1[2], s[7 * 33] * g1[3]);
;         const int wr_ = rowmap<MAP>(n0 + n), slot_ = PERMW ? ((wr_ & ~31) + invperm32(wr_ & 31)) : wr_;
;         *(u32x4*)((char*)WT + tiled_off(slot_, k0 + 8 * c, K / 64)) = o; }
;     asm volatile("s_waitcnt lgkmcnt(0)" ::: "memory");
; }
; template <int MAP, bool HASG = false, bool PERMW = false>
; __device__ __forceinline__ void transpose_mat(const float* W, int K, int N, bf16_t* WT, LAS float* scr, int gw, int ngw, int lane, const float* gk = nullptr) {
;     const int nitems = (K / 64) * (N / 32);
;     int it = gw;
;     if (it >= nitems) return;
;     float wv[32];
;     tr_load(W, N, it, lane, wv);
;     for (;;) {
;         __builtin_amdgcn_sched_barrier(0);
; #pragma unroll
;         for (int i = 0; i < 32; ++i) { const int kk = 2 * i + (lane >> 5); scr[kk * 33 + (lane & 31)] = wv[i]; }
;         __builtin_amdgcn_sched_barrier(0);
;         const int nx = it + ngw;
;         if (nx < nitems) tr_load(W, N, nx, lane, wv);
;         __builtin_amdgcn_sched_barrier(0);
;         tr_store<MAP, HASG, PERMW>(K, N, WT, scr, it, lane, gk);
;         if (nx >= nitems) break;
;         it = nx;
;     }
; }
.Ltc2b_exit:
	v_readlane_b32 s4, v255, 2
	v_readlane_b32 s5, v255, 3
	v_readlane_b32 s20, v254, 62
	v_readlane_b32 s21, v254, 63
	s_nop 3
	s_andn2_b32 s6, 0x2c00000, s60
	s_add_u32 s4, s4, s6
	s_addc_u32 s5, s5, 0
	s_andn2_b32 s6, 0x2000, s60
	s_add_u32 s20, s20, s6
	s_addc_u32 s21, s21, 0
	s_add_u32 s6, s76, 0x0
	s_addc_u32 s7, s77, 0
	s_mov_b32 s9, s18
	s_cmpk_ge_u32 s9, 0x1600
	s_cbranch_scc1 .Ltc2c_exit
	s_mul_hi_u32 s11, s9, 0x2e8ba2e9
	s_lshr_b32 s11, s11, 5
	s_mul_i32 s12, s11, 0xb0
	s_sub_u32 s12, s9, s12
	s_mul_i32 s13, s11, 0x160000
	s_lshl_b32 s14, s12, 7
	s_add_u32 s13, s13, s14
	s_add_u32 s14, s4, s13
	s_addc_u32 s15, s5, 0
	global_load_dword v16, v15, s[14:15] nt
	s_add_u32 s14, s14, 0xb000
	s_addc_u32 s15, s15, 0
	global_load_dword v17, v15, s[14:15] nt
	s_add_u32 s14, s14, 0xb000
	s_addc_u32 s15, s15, 0
	global_load_dword v18, v15, s[14:15] nt
	s_add_u32 s14, s14, 0xb000
	s_addc_u32 s15, s15, 0
	global_load_dword v19, v15, s[14:15] nt
	s_add_u32 s14, s14, 0xb000
	s_addc_u32 s15, s15, 0
	global_load_dword v20, v15, s[14:15] nt
	s_add_u32 s14, s14, 0xb000
	s_addc_u32 s15, s15, 0
	global_load_dword v21, v15, s[14:15] nt
	s_add_u32 s14, s14, 0xb000
	s_addc_u32 s15, s15, 0
	global_load_dword v22, v15, s[14:15] nt
	s_add_u32 s14, s14, 0xb000
	s_addc_u32 s15, s15, 0
	global_load_dword v23, v15, s[14:15] nt
	s_add_u32 s14, s14, 0xb000
	s_addc_u32 s15, s15, 0
	global_load_dword v24, v15, s[14:15] nt
	s_add_u32 s14, s14, 0xb000
	s_addc_u32 s15, s15, 0
	global_load_dword v25, v15, s[14:15] nt
	s_add_u32 s14, s14, 0xb000
	s_addc_u32 s15, s15, 0
	global_load_dword v26, v15, s[14:15] nt
	s_add_u32 s14, s14, 0xb000
	s_addc_u32 s15, s15, 0
	global_load_dword v27, v15, s[14:15] nt
	s_add_u32 s14, s14, 0xb000
	s_addc_u32 s15, s15, 0
	global_load_dword v28, v15, s[14:15] nt
	s_add_u32 s14, s14, 0xb000
	s_addc_u32 s15, s15, 0
	global_load_dword v29, v15, s[14:15] nt
	s_add_u32 s14, s14, 0xb000
	s_addc_u32 s15, s15, 0
	global_load_dword v30, v15, s[14:15] nt
	s_add_u32 s14, s14, 0xb000
	s_addc_u32 s15, s15, 0
	global_load_dword v31, v15, s[14:15] nt
	s_add_u32 s14, s14, 0xb000
	s_addc_u32 s15, s15, 0
	global_load_dword v32, v15, s[14:15] nt
	s_add_u32 s14, s14, 0xb000
	s_addc_u32 s15, s15, 0
	global_load_dword v33, v15, s[14:15] nt
	s_add_u32 s14, s14, 0xb000
	s_addc_u32 s15, s15, 0
	global_load_dword v34, v15, s[14:15] nt
	s_add_u32 s14, s14, 0xb000
	s_addc_u32 s15, s15, 0
	global_load_dword v35, v15, s[14:15] nt
	s_add_u32 s14, s14, 0xb000
	s_addc_u32 s15, s15, 0
	global_load_dword v36, v15, s[14:15] nt
	s_add_u32 s14, s14, 0xb000
	s_addc_u32 s15, s15, 0
	global_load_dword v37, v15, s[14:15] nt
	s_add_u32 s14, s14, 0xb000
	s_addc_u32 s15, s15, 0
	global_load_dword v38, v15, s[14:15] nt
	s_add_u32 s14, s14, 0xb000
	s_addc_u32 s15, s15, 0
	global_load_dword v39, v15, s[14:15] nt
	s_add_u32 s14, s14, 0xb000
	s_addc_u32 s15, s15, 0
	global_load_dword v40, v15, s[14:15] nt
	s_add_u32 s14, s14, 0xb000
	s_addc_u32 s15, s15, 0
	global_load_dword v41, v15, s[14:15] nt
	s_add_u32 s14, s14, 0xb000
	s_addc_u32 s15, s15, 0
	global_load_dword v42, v15, s[14:15] nt
	s_add_u32 s14, s14, 0xb000
	s_addc_u32 s15, s15, 0
	global_load_dword v43, v15, s[14:15] nt
	s_add_u32 s14, s14, 0xb000
	s_addc_u32 s15, s15, 0
	global_load_dword v44, v15, s[14:15] nt
	s_add_u32 s14, s14, 0xb000
	s_addc_u32 s15, s15, 0
	global_load_dword v45, v15, s[14:15] nt
	s_add_u32 s14, s14, 0xb000
	s_addc_u32 s15, s15, 0
	global_load_dword v46, v15, s[14:15] nt
	s_add_u32 s14, s14, 0xb000
	s_addc_u32 s15, s15, 0
	global_load_dword v47, v15, s[14:15] nt
	s_lshl_b32 s14, s11, 8
	s_add_u32 s14, s20, s14
	s_addc_u32 s15, s21, 0
	global_load_dwordx4 v[80:83], v14, s[14:15]
	global_load_dwordx4 v[84:87], v14, s[14:15] offset:16
	s_lshr_b32 s16, s12, 2
	s_lshl_b32 s16, s16, 1
	s_add_u32 s16, s16, 1
	s_lshl_b32 s16, s16, 5
	s_add_u32 s16, s16, s11
	s_lshl_b32 s16, s16, 14
	s_and_b32 s17, s12, 3
	s_lshl_b32 s17, s17, 12
	s_add_u32 s16, s16, s17
	s_add_u32 s16, s6, s16
	s_addc_u32 s17, s7, 0

; #define LAS __attribute__((address_space(3)))
; __device__ __forceinline__ unsigned pk2(float lo, float hi) { f32x2 f = {lo, hi}; bf16x2_t b = __builtin_convertvector(f, bf16x2_t); return __builtin_bit_cast(unsigned, b); }
; __device__ __forceinline__ unsigned xb_xcc_id() { return (unsigned)__builtin_amdgcn_s_getreg((3 << 11) | 20) & 0xFu; }
; __device__ __forceinline__ void xcd_barrier(unsigned char* ws_base, volatile LAS unsigned* st) {
;     asm volatile("s_waitcnt vmcnt(0)" ::: "memory");
;     __syncthreads();
;     if (threadIdx.x == 0) {
;         unsigned long long a = (unsigned long long)(ws_base + WS_CTL);
;         asm volatile("" : "+s"(a));
;         unsigned* bar = (unsigned*)a;
;         const unsigned x = xb_xcc_id();
;         __builtin_amdgcn_s_waitcnt(0);
;         unsigned nloc = st[0], nx = st[1];
;         if (nloc == 0u) { xcd_barrier_complete(bar, x, nloc, nx); st[0] = nloc; st[1] = nx; }
; template <int MAP, bool HASG, bool PERMW>
; __device__ __forceinline__ void tr_store(int K, int N, bf16_t* WT, LAS float* scr, int item, int lane, const float* gk) {
;     const int nblk = N / 32, kb = item / nblk, nb = item % nblk, k0 = 64 * kb, n0 = 32 * nb;
;     asm volatile("s_waitcnt lgkmcnt(0)" ::: "memory");
;     const int c = lane & 7;
;     f32x4 g0 = {1.f, 1.f, 1.f, 1.f}, g1 = {1.f, 1.f, 1.f, 1.f};
;     if (HASG) { g0 = *(const f32x4*)(gk + k0 + 8 * c); g1 = *(const f32x4*)(gk + k0 + 8 * c + 4); }
; #pragma unroll
;     for (int j = 0; j < 4; ++j) { const int n = (lane >> 3) + 8 * j; const LAS float* s = scr + (8 * c) * 33 + n;
;         u32x4 o; o.x = pk2(s[0 * 33] * g0[0], s[1 * 33] * g0[1]); o.y = pk2(s[2 * 33] * g0[2], s[3 * 33] * g0[3]); o.z = pk2(s[4 * 33] * g1[0], s[5 * 33] * g1[1]); o.w = pk2(s[6 * 33] * g1[2], s[7 * 33] * g1[3]);
;         const int wr_ = rowmap<MAP>(n0 + n), slot_ = PERMW ? ((wr_ & ~31) + invperm32(wr_ & 31)) : wr_;
;         *(u32x4*)((char*)WT + tiled_off(slot_, k0 + 8 * c, K / 64)) = o; }
;     asm volatile("s_waitcnt lgkmcnt(0)" ::: "memory");
; }
.Ltc2c_lastB:
	s_waitcnt vmcnt(0)
	ds_write_b32 v4, v88
	ds_write_b32 v4, v89 offset:264
	ds_write_b32 v4, v90 offset:528
	ds_write_b32 v4, v91 offset:792
	ds_write_b32 v4, v92 offset:1056
	ds_write_b32 v4, v93 offset:1320
	ds_write_b32 v4, v94 offset:1584
	ds_write_b32 v4, v95 offset:1848
	ds_write_b32 v4, v96 offset:2112
	ds_write_b32 v4, v97 offset:2376
	ds_write_b32 v4, v98 offset:2640
	ds_write_b32 v4, v99 offset:2904
	ds_write_b32 v4, v100 offset:3168
	ds_write_b32 v4, v101 offset:3432
	ds_write_b32 v4, v102 offset:3696
	ds_write_b32 v4, v103 offset:3960
	ds_write_b32 v4, v104 offset:4224
	ds_write_b32 v4, v105 offset:4488
	ds_write_b32 v4, v106 offset:4752
	ds_write_b32 v4, v107 offset:5016
	ds_write_b32 v4, v108 offset:5280
	ds_write_b32 v4, v109 offset:5544
	ds_write_b32 v4, v110 offset:5808
	ds_write_b32 v4, v111 offset:6072
	ds_write_b32 v4, v112 offset:6336
	ds_write_b32 v4, v113 offset:6600
	ds_write_b32 v4, v114 offset:6864
	ds_write_b32 v4, v115 offset:7128
	ds_write_b32 v4, v116 offset:7392
	ds_write_b32 v4, v117 offset:7656
	ds_write_b32 v4, v118 offset:7920
	ds_write_b32 v4, v119 offset:8184
	s_waitcnt lgkmcnt(0)
	ds_read_b32 v48, v7
	ds_read_b32 v49, v7 offset:132
	ds_read_b32 v50, v7 offset:264
	ds_read_b32 v51, v7 offset:396
	ds_read_b32 v52, v7 offset:528
	ds_read_b32 v53, v7 offset:660
	ds_read_b32 v54, v7 offset:792
	ds_read_b32 v55, v7 offset:924
	ds_read_b32 v56, v7 offset:32
	ds_read_b32 v57, v7 offset:164
	ds_read_b32 v58, v7 offset:296
	ds_read_b32 v59, v7 offset:428
	ds_read_b32 v60, v7 offset:560
	ds_read_b32 v61, v7 offset:692
	ds_read_b32 v62, v7 offset:824
	ds_read_b32 v63, v7 offset:956
	ds_read_b32 v64, v7 offset:64
	ds_read_b32 v65, v7 offset:196
	ds_read_b32 v66, v7 offset:328
	ds_read_b32 v67, v7 offset:460
	ds_read_b32 v68, v7 offset:592
	ds_read_b32 v69, v7 offset:724
	ds_read_b32 v70, v7 offset:856
	ds_read_b32 v71, v7 offset:988
	ds_read_b32 v72, v7 offset:96
	ds_read_b32 v73, v7 offset:228
	ds_read_b32 v74, v7 offset:360
	ds_read_b32 v75, v7 offset:492
	ds_read_b32 v76, v7 offset:624
	ds_read_b32 v77, v7 offset:756
	ds_read_b32 v78, v7 offset:888
	ds_read_b32 v79, v7 offset:1020
	s_waitcnt lgkmcnt(0)
	v_mul_f32_e32 v48, v48, v120
	v_mul_f32_e32 v49, v49, v121
	v_mul_f32_e32 v50, v50, v122
	v_mul_f32_e32 v51, v51, v123
	v_mul_f32_e32 v52, v52, v124
	v_mul_f32_e32 v53, v53, v125
	v_mul_f32_e32 v54, v54, v126
	v_mul_f32_e32 v55, v55, v127
	v_cvt_pk_bf16_f32 v48, v48, v49
	v_cvt_pk_bf16_f32 v49, v50, v51
	v_cvt_pk_bf16_f32 v50, v52, v53
	v_cvt_pk_bf16_f32 v51, v54, v55
	global_store_dwordx4 v10, v[48:51], s[24:25]
	v_mul_f32_e32 v56, v56, v120
	v_mul_f32_e32 v57, v57, v121
	v_mul_f32_e32 v58, v58, v122
	v_mul_f32_e32 v59, v59, v123
	v_mul_f32_e32 v60, v60, v124
	v_mul_f32_e32 v61, v61, v125
	v_mul_f32_e32 v62, v62, v126
	v_mul_f32_e32 v63, v63, v127
	v_cvt_pk_bf16_f32 v56, v56, v57
	v_cvt_pk_bf16_f32 v57, v58, v59
	v_cvt_pk_bf16_f32 v58, v60, v61
	v_cvt_pk_bf16_f32 v59, v62, v63
	global_store_dwordx4 v10, v[56:59], s[24:25] offset:256
	v_mul_f32_e32 v64, v64, v120
	v_mul_f32_e32 v65, v65, v121
	v_mul_f32_e32 v66, v66, v122
	v_mul_f32_e32 v67, v67, v123
	v_mul_f32_e32 v68, v68, v124
	v_mul_f32_e32 v69, v69, v125
	v_mul_f32_e32 v70, v70, v126
	v_mul_f32_e32 v71, v71, v127
	v_cvt_pk_bf16_f32 v64, v64, v65
	v_cvt_pk_bf16_f32 v65, v66, v67
	v_cvt_pk_bf16_f32 v66, v68, v69
	v_cvt_pk_bf16_f32 v67, v70, v71
	global_store_dwordx4 v11, v[64:67], s[24:25] offset:512
	v_mul_f32_e32 v72, v72, v120
	v_mul_f32_e32 v73, v73, v121
	v_mul_f32_e32 v74, v74, v122
	v_mul_f32_e32 v75, v75, v123
	v_mul_f32_e32 v76, v76, v124
	v_mul_f32_e32 v77, v77, v125
	v_mul_f32_e32 v78, v78, v126
	v_mul_f32_e32 v79, v79, v127
	v_cvt_pk_bf16_f32 v72, v72, v73
	v_cvt_pk_bf16_f32 v73, v74, v75
	v_cvt_pk_bf16_f32 v74, v76, v77
	v_cvt_pk_bf16_f32 v75, v78, v79
	global_store_dwordx4 v11, v[72:75], s[24:25] offset:768
.Ltc2c_exit:
.Ltc2_nonext:
	v_readlane_b32 s4, v255, 24
	v_readlane_b32 s5, v255, 25
	v_readlane_b32 s6, v255, 26
	v_readlane_b32 s7, v255, 27
	v_readlane_b32 s8, v255, 28
	v_readlane_b32 s9, v255, 29
	v_readlane_b32 s10, v255, 30
	v_readlane_b32 s11, v255, 31
	v_readlane_b32 s12, v255, 32
	v_readlane_b32 s13, v255, 33
	v_readlane_b32 s14, v255, 34
	v_readlane_b32 s15, v255, 35
	v_readlane_b32 s16, v255, 36
	v_readlane_b32 s17, v255, 37
	v_readlane_b32 s18, v255, 38
	v_readlane_b32 s19, v255, 39
	v_readlane_b32 s20, v255, 40
	v_readlane_b32 s21, v255, 41
	v_readlane_b32 s22, v255, 42
	v_readlane_b32 s23, v255, 43
	v_readlane_b32 s24, v255, 44
	v_readlane_b32 s25, v255, 45
	v_readlane_b32 s26, v255, 46
	v_readlane_b32 s27, v255, 47
	v_readlane_b32 s28, v255, 48
	v_readlane_b32 s29, v255, 49
	s_nop 3
.Ltc2_done:
	s_waitcnt vmcnt(0)
	s_waitcnt vmcnt(0)
	s_barrier
	s_mov_b64 s[38:39], exec
	v_readlane_b32 s0, v254, 16
	v_readlane_b32 s1, v254, 17
	s_and_b64 s[0:1], s[38:39], s[0:1]
	s_mov_b64 exec, s[0:1]
	s_cbranch_execz .LBB0_870
	v_readlane_b32 s1, v255, 17
	s_mov_b64 s[40:41], s[96:97]
	s_getreg_b32 s0, hwreg(HW_REG_XCC_ID, 0, 4)
	v_mov_b32_e32 v0, s1
	s_waitcnt vmcnt(0) expcnt(0) lgkmcnt(0)
	ds_read_b32 v2, v0
	v_readlane_b32 s1, v255, 18
	s_and_b32 s4, s0, 15
	s_waitcnt lgkmcnt(0)
	v_cmp_ne_u32_e32 vcc, 0, v2
	v_mov_b32_e32 v0, s1
	ds_read_b32 v0, v0
	s_cbranch_vccnz .LBB0_841
	s_add_u32 s0, s40, 0x1000
	s_addc_u32 s1, s41, 0
	s_add_u32 s6, s40, 0x1100
	s_addc_u32 s7, s41, 0
	s_add_u32 s8, s40, 0x1200
	s_addc_u32 s9, s41, 0
	s_add_u32 s10, s40, 0x1300
	s_addc_u32 s11, s41, 0
	s_mov_b32 s5, 1
	s_mov_b64 s[14:15], 0
	s_branch .LBB0_831
